# attention PV block re-ordered k-step-outer with the next k-step's exp/cvt software-pipelined under the current step's MFMAs; V fragments double-buffered
# speedup vs baseline: 1.0062x; 1.0030x over previous
.LBB0_582:
	v_lshl_add_u32 v188, s81, 14, v152
	ds_read_b64_tr_b16 v[172:173], v188 offset:0
	ds_read_b64_tr_b16 v[174:175], v188 offset:512
	ds_read_b64_tr_b16 v[176:177], v188 offset:4096
	ds_read_b64_tr_b16 v[178:179], v188 offset:4608
	ds_read_b64_tr_b16 v[180:181], v188 offset:8192
	ds_read_b64_tr_b16 v[182:183], v188 offset:8704
	ds_read_b64_tr_b16 v[184:185], v188 offset:12288
	ds_read_b64_tr_b16 v[186:187], v188 offset:12800
	ds_read_b64_tr_b16 v[192:193], v188 offset:1024
	ds_read_b64_tr_b16 v[194:195], v188 offset:1536
	ds_read_b64_tr_b16 v[196:197], v188 offset:5120
	ds_read_b64_tr_b16 v[198:199], v188 offset:5632
	ds_read_b64_tr_b16 v[200:201], v188 offset:9216
	ds_read_b64_tr_b16 v[202:203], v188 offset:9728
	ds_read_b64_tr_b16 v[204:205], v188 offset:13312
	ds_read_b64_tr_b16 v[206:207], v188 offset:13824
	v_exp_f32_e32 v66, v66
	v_exp_f32_e32 v67, v67
	v_exp_f32_e32 v68, v68
	v_exp_f32_e32 v69, v69
	v_exp_f32_e32 v70, v70
	v_exp_f32_e32 v71, v71
	v_exp_f32_e32 v72, v72
	v_exp_f32_e32 v73, v73
	v_cvt_pk_bf16_f32 v156, v66, v67
	v_cvt_pk_bf16_f32 v157, v68, v69
	v_cvt_pk_bf16_f32 v158, v70, v71
	v_cvt_pk_bf16_f32 v159, v72, v73
	s_waitcnt lgkmcnt(8)
	s_nop 1
	v_mfma_f32_32x32x16_bf16 v[2:17], v[156:159], v[172:175], v[2:17]
	v_exp_f32_e32 v74, v74
	v_exp_f32_e32 v75, v75
	v_mfma_f32_32x32x16_bf16 v[50:65], v[156:159], v[176:179], v[50:65]
	v_exp_f32_e32 v76, v76
	v_exp_f32_e32 v77, v77
	v_mfma_f32_32x32x16_bf16 v[34:49], v[156:159], v[180:183], v[34:49]
	v_exp_f32_e32 v78, v78
	v_exp_f32_e32 v79, v79
	v_mfma_f32_32x32x16_bf16 v[18:33], v[156:159], v[184:187], v[18:33]
	v_exp_f32_e32 v80, v80
	v_exp_f32_e32 v81, v81
	v_cvt_pk_bf16_f32 v160, v74, v75
	v_cvt_pk_bf16_f32 v161, v76, v77
	v_cvt_pk_bf16_f32 v162, v78, v79
	v_cvt_pk_bf16_f32 v163, v80, v81
	ds_read_b64_tr_b16 v[172:173], v188 offset:2048
	ds_read_b64_tr_b16 v[174:175], v188 offset:2560
	ds_read_b64_tr_b16 v[176:177], v188 offset:6144
	ds_read_b64_tr_b16 v[178:179], v188 offset:6656
	ds_read_b64_tr_b16 v[180:181], v188 offset:10240
	ds_read_b64_tr_b16 v[182:183], v188 offset:10752
	ds_read_b64_tr_b16 v[184:185], v188 offset:14336
	ds_read_b64_tr_b16 v[186:187], v188 offset:14848
	s_waitcnt lgkmcnt(8)
	s_nop 1
	v_mfma_f32_32x32x16_bf16 v[2:17], v[160:163], v[192:195], v[2:17]
	v_exp_f32_e32 v82, v82
	v_exp_f32_e32 v83, v83
	v_mfma_f32_32x32x16_bf16 v[50:65], v[160:163], v[196:199], v[50:65]
	v_exp_f32_e32 v84, v84
	v_exp_f32_e32 v85, v85
	v_mfma_f32_32x32x16_bf16 v[34:49], v[160:163], v[200:203], v[34:49]
	v_exp_f32_e32 v86, v86
	v_exp_f32_e32 v87, v87
	v_mfma_f32_32x32x16_bf16 v[18:33], v[160:163], v[204:207], v[18:33]
	v_exp_f32_e32 v88, v88
	v_exp_f32_e32 v89, v89
	v_cvt_pk_bf16_f32 v164, v82, v83
	v_cvt_pk_bf16_f32 v165, v84, v85
	v_cvt_pk_bf16_f32 v166, v86, v87
	v_cvt_pk_bf16_f32 v167, v88, v89
	ds_read_b64_tr_b16 v[192:193], v188 offset:3072
	ds_read_b64_tr_b16 v[194:195], v188 offset:3584
	ds_read_b64_tr_b16 v[196:197], v188 offset:7168
	ds_read_b64_tr_b16 v[198:199], v188 offset:7680
	ds_read_b64_tr_b16 v[200:201], v188 offset:11264
	ds_read_b64_tr_b16 v[202:203], v188 offset:11776
	ds_read_b64_tr_b16 v[204:205], v188 offset:15360
	ds_read_b64_tr_b16 v[206:207], v188 offset:15872
	s_waitcnt lgkmcnt(8)
	s_nop 1
	v_mfma_f32_32x32x16_bf16 v[2:17], v[164:167], v[172:175], v[2:17]
	v_exp_f32_e32 v90, v90
	v_exp_f32_e32 v91, v91
	v_mfma_f32_32x32x16_bf16 v[50:65], v[164:167], v[176:179], v[50:65]
	v_exp_f32_e32 v92, v92
	v_exp_f32_e32 v93, v93
	v_mfma_f32_32x32x16_bf16 v[34:49], v[164:167], v[180:183], v[34:49]
	v_exp_f32_e32 v94, v94
	v_exp_f32_e32 v95, v95
	v_mfma_f32_32x32x16_bf16 v[18:33], v[164:167], v[184:187], v[18:33]
	v_exp_f32_e32 v96, v96
	v_exp_f32_e32 v97, v97
	v_cvt_pk_bf16_f32 v168, v90, v91
	v_cvt_pk_bf16_f32 v169, v92, v93
	v_cvt_pk_bf16_f32 v170, v94, v95
	v_cvt_pk_bf16_f32 v171, v96, v97
	s_waitcnt lgkmcnt(0)
	s_nop 1
	v_mfma_f32_32x32x16_bf16 v[2:17], v[168:171], v[192:195], v[2:17]
	s_cmp_lt_u32 s83, 3
	v_mfma_f32_32x32x16_bf16 v[50:65], v[168:171], v[196:199], v[50:65]
	s_cselect_b64 s[8:9], -1, 0
	v_mfma_f32_32x32x16_bf16 v[34:49], v[168:171], v[200:203], v[34:49]
	s_or_b64 s[0:1], s[8:9], s[0:1]
	v_mfma_f32_32x32x16_bf16 v[18:33], v[168:171], v[204:207], v[18:33]
	s_and_b64 vcc, exec, s[0:1]
	s_cbranch_vccnz .LBB0_586
	v_cvt_f32_i32_e32 v156, v153
	v_fma_f32 v156, v117, v156, v150
	v_sub_f32_e32 v156, v156, v155
	s_nop 1
	v_max_f32_dpp v156, v156, v156 row_ror:1 row_mask:0xf bank_mask:0xf
	s_nop 1
	v_max_f32_dpp v156, v156, v156 row_ror:2 row_mask:0xf bank_mask:0xf
	s_nop 1
	v_max_f32_dpp v156, v156, v156 row_ror:4 row_mask:0xf bank_mask:0xf
	s_nop 1
	v_max_f32_dpp v156, v156, v156 row_ror:8 row_mask:0xf bank_mask:0xf
	s_nop 1
	v_readlane_b32 s9, v156, 16
	s_and_saveexec_b64 s[0:1], s[6:7]
	s_cbranch_execz .LBB0_585
	s_and_b32 s8, s80, 8
	s_lshl_b32 s8, s8, 2
	s_add_i32 s8, s68, s8
	v_max_f32_e32 v156, s9, v156
	v_mov_b32_e32 v157, s8
	ds_write_b32 v157, v156
